# v10 + mLSTM output item prologue: NK and all 32 Q rows loaded in one batch (was 8 serialized round trips)
# baseline (speedup 1.0000x reference)
.LBB0_615:
	s_lshl_b32 s0, s18, 6
	s_lshl_b32 s1, s18, 8
	s_and_b32 s0, s0, 0xffffe000
	s_and_b32 s1, s1, 0x1f00
	s_or_b32 s20, s0, s1
	s_ashr_i32 s19, s18, 31
	s_bfe_u32 s33, s18, 0x20005
	s_ashr_i32 s21, s20, 31
	s_lshl_b64 s[0:1], s[18:19], 2
	s_add_u32 s0, s37, s0
	s_addc_u32 s1, s38, s1
	v_readfirstlane_b32 s81, v182
	global_load_dword v2, v153, s[0:1]
	s_lshl_b64 s[22:23], s[18:19], 10
	s_add_u32 s22, s39, s22
	s_addc_u32 s23, s40, s23
	v_and_b32_e32 v4, 63, v182
	v_lshlrev_b32_e32 v5, 4, v4
	v_lshlrev_b32_e32 v152, 3, v4
	global_load_dwordx4 v[74:77], v5, s[22:23]
	s_ashr_i32 s2, s81, 6
	s_lshl_b64 s[22:23], s[20:21], 11
	s_lshl_b32 s24, s2, 16
	s_add_u32 s22, s22, s24
	s_addc_u32 s23, s23, 0
	s_lshl_b32 s25, s33, 9
	s_add_u32 s22, s22, s25
	s_addc_u32 s23, s23, 0
	s_add_u32 s22, s22, s65
	s_addc_u32 s23, s23, s68
	s_sub_u32 s22, s22, 0x3800
	s_subb_u32 s23, s23, 0
	global_load_dwordx2 v[10:11], v152, s[22:23] offset:0
	global_load_dwordx2 v[12:13], v152, s[22:23] offset:2048
	s_add_u32 s22, s22, 0x1000
	s_addc_u32 s23, s23, 0
	global_load_dwordx2 v[14:15], v152, s[22:23] offset:0
	global_load_dwordx2 v[16:17], v152, s[22:23] offset:2048
	s_add_u32 s22, s22, 0x1000
	s_addc_u32 s23, s23, 0
	global_load_dwordx2 v[18:19], v152, s[22:23] offset:0
	global_load_dwordx2 v[20:21], v152, s[22:23] offset:2048
	s_add_u32 s22, s22, 0x1000
	s_addc_u32 s23, s23, 0
	global_load_dwordx2 v[22:23], v152, s[22:23] offset:0
	global_load_dwordx2 v[24:25], v152, s[22:23] offset:2048
	s_add_u32 s22, s22, 0x1000
	s_addc_u32 s23, s23, 0
	global_load_dwordx2 v[26:27], v152, s[22:23] offset:0
	global_load_dwordx2 v[28:29], v152, s[22:23] offset:2048
	s_add_u32 s22, s22, 0x1000
	s_addc_u32 s23, s23, 0
	global_load_dwordx2 v[30:31], v152, s[22:23] offset:0
	global_load_dwordx2 v[32:33], v152, s[22:23] offset:2048
	s_add_u32 s22, s22, 0x1000
	s_addc_u32 s23, s23, 0
	global_load_dwordx2 v[34:35], v152, s[22:23] offset:0
	global_load_dwordx2 v[36:37], v152, s[22:23] offset:2048
	s_add_u32 s22, s22, 0x1000
	s_addc_u32 s23, s23, 0
	global_load_dwordx2 v[38:39], v152, s[22:23] offset:0
	global_load_dwordx2 v[40:41], v152, s[22:23] offset:2048
	s_add_u32 s22, s22, 0x1000
	s_addc_u32 s23, s23, 0
	global_load_dwordx2 v[42:43], v152, s[22:23] offset:0
	global_load_dwordx2 v[44:45], v152, s[22:23] offset:2048
	s_add_u32 s22, s22, 0x1000
	s_addc_u32 s23, s23, 0
	global_load_dwordx2 v[46:47], v152, s[22:23] offset:0
	global_load_dwordx2 v[48:49], v152, s[22:23] offset:2048
	s_add_u32 s22, s22, 0x1000
	s_addc_u32 s23, s23, 0
	global_load_dwordx2 v[50:51], v152, s[22:23] offset:0
	global_load_dwordx2 v[52:53], v152, s[22:23] offset:2048
	s_add_u32 s22, s22, 0x1000
	s_addc_u32 s23, s23, 0
	global_load_dwordx2 v[54:55], v152, s[22:23] offset:0
	global_load_dwordx2 v[56:57], v152, s[22:23] offset:2048
	s_add_u32 s22, s22, 0x1000
	s_addc_u32 s23, s23, 0
	global_load_dwordx2 v[58:59], v152, s[22:23] offset:0
	global_load_dwordx2 v[60:61], v152, s[22:23] offset:2048
	s_add_u32 s22, s22, 0x1000
	s_addc_u32 s23, s23, 0
	global_load_dwordx2 v[62:63], v152, s[22:23] offset:0
	global_load_dwordx2 v[64:65], v152, s[22:23] offset:2048
	s_add_u32 s22, s22, 0x1000
	s_addc_u32 s23, s23, 0
	global_load_dwordx2 v[66:67], v152, s[22:23] offset:0
	global_load_dwordx2 v[68:69], v152, s[22:23] offset:2048
	s_add_u32 s22, s22, 0x1000
	s_addc_u32 s23, s23, 0
	global_load_dwordx2 v[70:71], v152, s[22:23] offset:0
	global_load_dwordx2 v[72:73], v152, s[22:23] offset:2048
	s_movk_i32 s0, 0x100
	v_mov_b32_e32 v1, v182
	v_cmp_gt_i32_e32 vcc, s0, v1
	s_barrier
	s_and_saveexec_b64 s[0:1], vcc
	s_cbranch_execz .LBB0_617
	v_add_u32_e32 v4, s20, v1
	v_ashrrev_i32_e32 v5, 31, v4
	v_lshlrev_b64 v[4:5], 4, v[4:5]
	v_lshl_or_b32 v4, s33, 2, v4
	v_lshl_add_u64 v[6:7], s[8:9], 0, v[4:5]
	global_load_dword v3, v[6:7], off
	v_lshl_add_u64 v[6:7], s[4:5], 0, v[4:5]
	global_load_dword v6, v[6:7], off
	v_lshl_add_u64 v[4:5], s[6:7], 0, v[4:5]
	global_load_dword v4, v[4:5], off
	s_waitcnt vmcnt(0)
	v_max_f32_e32 v5, v2, v2
	v_lshl_add_u32 v1, v1, 2, 0
	v_add_u32_e32 v9, 0x20800, v1
	v_add_u32_e32 v7, 0x20000, v1
	v_add_u32_e32 v8, 0x20400, v1
	v_add_u32_e32 v1, 0x20c00, v1
	s_waitcnt vmcnt(2)
	v_max_f32_e32 v3, v3, v3
	v_max_f32_e32 v3, v5, v3
	v_sub_f32_e32 v2, v2, v3
	s_waitcnt vmcnt(1)
	v_add_f32_e32 v5, v6, v3
	v_mul_f32_e32 v2, 0x3fb8aa3b, v2
	v_mul_f32_e32 v5, 0xbfb8aa3b, v5
	v_exp_f32_e32 v2, v2
	v_exp_f32_e32 v5, v5
	s_waitcnt vmcnt(0)
	ds_write_b32 v9, v4
	ds_write_b32 v7, v3
	ds_write_b32 v8, v2
	ds_write_b32 v1, v5
.LBB0_617:
	s_or_b64 exec, exec, s[0:1]
	s_lshl_b32 s24, s2, 7
	s_add_i32 s24, s24, 0x21000
	s_mov_b64 s[26:27], 1
	s_waitcnt vmcnt(28)
	v_and_b32_e32 v78, 0xffff0000, v10
	v_lshlrev_b32_e32 v10, 16, v10
	v_mul_f32_e32 v78, v75, v78
	v_fmac_f32_e32 v78, v74, v10
	v_lshlrev_b32_e32 v10, 16, v11
	v_fmac_f32_e32 v78, v76, v10
	v_and_b32_e32 v11, 0xffff0000, v11
	v_fmac_f32_e32 v78, v77, v11
	v_and_b32_e32 v79, 0xffff0000, v12
	v_lshlrev_b32_e32 v12, 16, v12
	v_mul_f32_e32 v79, v75, v79
	v_fmac_f32_e32 v79, v74, v12
	v_lshlrev_b32_e32 v12, 16, v13
	v_fmac_f32_e32 v79, v76, v12
	v_and_b32_e32 v13, 0xffff0000, v13
	v_fmac_f32_e32 v79, v77, v13
	v_and_b32_e32 v80, 0xffff0000, v14
	v_lshlrev_b32_e32 v14, 16, v14
	v_mul_f32_e32 v80, v75, v80
	v_fmac_f32_e32 v80, v74, v14
	v_lshlrev_b32_e32 v14, 16, v15
	v_fmac_f32_e32 v80, v76, v14
	v_and_b32_e32 v15, 0xffff0000, v15
	v_fmac_f32_e32 v80, v77, v15
	v_and_b32_e32 v81, 0xffff0000, v16
	v_lshlrev_b32_e32 v16, 16, v16
	v_mul_f32_e32 v81, v75, v81
	v_fmac_f32_e32 v81, v74, v16
	v_lshlrev_b32_e32 v16, 16, v17
	v_fmac_f32_e32 v81, v76, v16
	v_and_b32_e32 v17, 0xffff0000, v17
	v_fmac_f32_e32 v81, v77, v17
	v_add_f32_dpp v78, v78, v78 quad_perm:[1,0,3,2] row_mask:0xf bank_mask:0xf bound_ctrl:1
	v_add_f32_dpp v79, v79, v79 quad_perm:[1,0,3,2] row_mask:0xf bank_mask:0xf bound_ctrl:1
	v_add_f32_dpp v80, v80, v80 quad_perm:[1,0,3,2] row_mask:0xf bank_mask:0xf bound_ctrl:1
	v_add_f32_dpp v81, v81, v81 quad_perm:[1,0,3,2] row_mask:0xf bank_mask:0xf bound_ctrl:1
	v_add_f32_dpp v78, v78, v78 quad_perm:[2,3,0,1] row_mask:0xf bank_mask:0xf bound_ctrl:1
	v_add_f32_dpp v79, v79, v79 quad_perm:[2,3,0,1] row_mask:0xf bank_mask:0xf bound_ctrl:1
	v_add_f32_dpp v80, v80, v80 quad_perm:[2,3,0,1] row_mask:0xf bank_mask:0xf bound_ctrl:1
	v_add_f32_dpp v81, v81, v81 quad_perm:[2,3,0,1] row_mask:0xf bank_mask:0xf bound_ctrl:1
	v_add_f32_dpp v78, v78, v78 row_half_mirror row_mask:0xf bank_mask:0xf bound_ctrl:1
	v_add_f32_dpp v79, v79, v79 row_half_mirror row_mask:0xf bank_mask:0xf bound_ctrl:1
	v_add_f32_dpp v80, v80, v80 row_half_mirror row_mask:0xf bank_mask:0xf bound_ctrl:1
	v_add_f32_dpp v81, v81, v81 row_half_mirror row_mask:0xf bank_mask:0xf bound_ctrl:1
	v_add_f32_dpp v78, v78, v78 row_mirror row_mask:0xf bank_mask:0xf bound_ctrl:1
	v_add_f32_dpp v79, v79, v79 row_mirror row_mask:0xf bank_mask:0xf bound_ctrl:1
	v_add_f32_dpp v80, v80, v80 row_mirror row_mask:0xf bank_mask:0xf bound_ctrl:1
	v_add_f32_dpp v81, v81, v81 row_mirror row_mask:0xf bank_mask:0xf bound_ctrl:1
	v_readlane_b32 s82, v78, 0
	v_readlane_b32 s83, v78, 16
	v_readlane_b32 s84, v78, 32
	v_readlane_b32 s85, v78, 48
	v_readlane_b32 s86, v79, 0
	v_readlane_b32 s87, v79, 16
	v_readlane_b32 s88, v79, 32
	v_readlane_b32 s89, v79, 48
	v_readlane_b32 s90, v80, 0
	v_readlane_b32 s91, v80, 16
	v_readlane_b32 s92, v80, 32
	v_readlane_b32 s93, v80, 48
	v_readlane_b32 s94, v81, 0
	v_readlane_b32 s95, v81, 16
	v_readlane_b32 s79, v81, 32
	v_readlane_b32 s80, v81, 48
	s_mov_b64 exec, s[26:27]
	v_mov_b32_e32 v9, s83
	v_add_f32_e32 v9, s82, v9
	v_add_f32_e32 v9, s84, v9
	v_add_f32_e32 v9, s85, v9
	s_lshl_b64 s[26:27], s[26:27], 1
	s_mov_b64 exec, s[26:27]
	v_mov_b32_e32 v9, s87
	v_add_f32_e32 v9, s86, v9
	v_add_f32_e32 v9, s88, v9
	v_add_f32_e32 v9, s89, v9
	s_lshl_b64 s[26:27], s[26:27], 1
	s_mov_b64 exec, s[26:27]
	v_mov_b32_e32 v9, s91
	v_add_f32_e32 v9, s90, v9
	v_add_f32_e32 v9, s92, v9
	v_add_f32_e32 v9, s93, v9
	s_lshl_b64 s[26:27], s[26:27], 1
	s_mov_b64 exec, s[26:27]
	v_mov_b32_e32 v9, s95
	v_add_f32_e32 v9, s94, v9
	v_add_f32_e32 v9, s79, v9
	v_add_f32_e32 v9, s80, v9
	s_lshl_b64 s[26:27], s[26:27], 1
	s_mov_b64 exec, -1
	s_waitcnt vmcnt(24)
	v_and_b32_e32 v78, 0xffff0000, v18
	v_lshlrev_b32_e32 v18, 16, v18
	v_mul_f32_e32 v78, v75, v78
	v_fmac_f32_e32 v78, v74, v18
	v_lshlrev_b32_e32 v18, 16, v19
	v_fmac_f32_e32 v78, v76, v18
	v_and_b32_e32 v19, 0xffff0000, v19
	v_fmac_f32_e32 v78, v77, v19
	v_and_b32_e32 v79, 0xffff0000, v20
	v_lshlrev_b32_e32 v20, 16, v20
	v_mul_f32_e32 v79, v75, v79
	v_fmac_f32_e32 v79, v74, v20
	v_lshlrev_b32_e32 v20, 16, v21
	v_fmac_f32_e32 v79, v76, v20
	v_and_b32_e32 v21, 0xffff0000, v21
	v_fmac_f32_e32 v79, v77, v21
	v_and_b32_e32 v80, 0xffff0000, v22
	v_lshlrev_b32_e32 v22, 16, v22
	v_mul_f32_e32 v80, v75, v80
	v_fmac_f32_e32 v80, v74, v22
	v_lshlrev_b32_e32 v22, 16, v23
	v_fmac_f32_e32 v80, v76, v22
	v_and_b32_e32 v23, 0xffff0000, v23
	v_fmac_f32_e32 v80, v77, v23
	v_and_b32_e32 v81, 0xffff0000, v24
	v_lshlrev_b32_e32 v24, 16, v24
	v_mul_f32_e32 v81, v75, v81
	v_fmac_f32_e32 v81, v74, v24
	v_lshlrev_b32_e32 v24, 16, v25
	v_fmac_f32_e32 v81, v76, v24
	v_and_b32_e32 v25, 0xffff0000, v25
	v_fmac_f32_e32 v81, v77, v25
	v_add_f32_dpp v78, v78, v78 quad_perm:[1,0,3,2] row_mask:0xf bank_mask:0xf bound_ctrl:1
	v_add_f32_dpp v79, v79, v79 quad_perm:[1,0,3,2] row_mask:0xf bank_mask:0xf bound_ctrl:1
	v_add_f32_dpp v80, v80, v80 quad_perm:[1,0,3,2] row_mask:0xf bank_mask:0xf bound_ctrl:1
	v_add_f32_dpp v81, v81, v81 quad_perm:[1,0,3,2] row_mask:0xf bank_mask:0xf bound_ctrl:1
	v_add_f32_dpp v78, v78, v78 quad_perm:[2,3,0,1] row_mask:0xf bank_mask:0xf bound_ctrl:1
	v_add_f32_dpp v79, v79, v79 quad_perm:[2,3,0,1] row_mask:0xf bank_mask:0xf bound_ctrl:1
	v_add_f32_dpp v80, v80, v80 quad_perm:[2,3,0,1] row_mask:0xf bank_mask:0xf bound_ctrl:1
	v_add_f32_dpp v81, v81, v81 quad_perm:[2,3,0,1] row_mask:0xf bank_mask:0xf bound_ctrl:1
	v_add_f32_dpp v78, v78, v78 row_half_mirror row_mask:0xf bank_mask:0xf bound_ctrl:1
	v_add_f32_dpp v79, v79, v79 row_half_mirror row_mask:0xf bank_mask:0xf bound_ctrl:1
	v_add_f32_dpp v80, v80, v80 row_half_mirror row_mask:0xf bank_mask:0xf bound_ctrl:1
	v_add_f32_dpp v81, v81, v81 row_half_mirror row_mask:0xf bank_mask:0xf bound_ctrl:1
	v_add_f32_dpp v78, v78, v78 row_mirror row_mask:0xf bank_mask:0xf bound_ctrl:1
	v_add_f32_dpp v79, v79, v79 row_mirror row_mask:0xf bank_mask:0xf bound_ctrl:1
	v_add_f32_dpp v80, v80, v80 row_mirror row_mask:0xf bank_mask:0xf bound_ctrl:1
	v_add_f32_dpp v81, v81, v81 row_mirror row_mask:0xf bank_mask:0xf bound_ctrl:1
	v_readlane_b32 s82, v78, 0
	v_readlane_b32 s83, v78, 16
	v_readlane_b32 s84, v78, 32
	v_readlane_b32 s85, v78, 48
	v_readlane_b32 s86, v79, 0
	v_readlane_b32 s87, v79, 16
	v_readlane_b32 s88, v79, 32
	v_readlane_b32 s89, v79, 48
	v_readlane_b32 s90, v80, 0
	v_readlane_b32 s91, v80, 16
	v_readlane_b32 s92, v80, 32
	v_readlane_b32 s93, v80, 48
	v_readlane_b32 s94, v81, 0
	v_readlane_b32 s95, v81, 16
	v_readlane_b32 s79, v81, 32
	v_readlane_b32 s80, v81, 48
	s_mov_b64 exec, s[26:27]
	v_mov_b32_e32 v9, s83
	v_add_f32_e32 v9, s82, v9
	v_add_f32_e32 v9, s84, v9
	v_add_f32_e32 v9, s85, v9
	s_lshl_b64 s[26:27], s[26:27], 1
	s_mov_b64 exec, s[26:27]
	v_mov_b32_e32 v9, s87
	v_add_f32_e32 v9, s86, v9
	v_add_f32_e32 v9, s88, v9
	v_add_f32_e32 v9, s89, v9
	s_lshl_b64 s[26:27], s[26:27], 1
	s_mov_b64 exec, s[26:27]
	v_mov_b32_e32 v9, s91
	v_add_f32_e32 v9, s90, v9
	v_add_f32_e32 v9, s92, v9
	v_add_f32_e32 v9, s93, v9
	s_lshl_b64 s[26:27], s[26:27], 1
	s_mov_b64 exec, s[26:27]
	v_mov_b32_e32 v9, s95
	v_add_f32_e32 v9, s94, v9
	v_add_f32_e32 v9, s79, v9
	v_add_f32_e32 v9, s80, v9
	s_lshl_b64 s[26:27], s[26:27], 1
	s_mov_b64 exec, -1
	s_waitcnt vmcnt(20)
	v_and_b32_e32 v78, 0xffff0000, v26
	v_lshlrev_b32_e32 v26, 16, v26
	v_mul_f32_e32 v78, v75, v78
	v_fmac_f32_e32 v78, v74, v26
	v_lshlrev_b32_e32 v26, 16, v27
	v_fmac_f32_e32 v78, v76, v26
	v_and_b32_e32 v27, 0xffff0000, v27
	v_fmac_f32_e32 v78, v77, v27
	v_and_b32_e32 v79, 0xffff0000, v28
	v_lshlrev_b32_e32 v28, 16, v28
	v_mul_f32_e32 v79, v75, v79
	v_fmac_f32_e32 v79, v74, v28
	v_lshlrev_b32_e32 v28, 16, v29
	v_fmac_f32_e32 v79, v76, v28
	v_and_b32_e32 v29, 0xffff0000, v29
	v_fmac_f32_e32 v79, v77, v29
	v_and_b32_e32 v80, 0xffff0000, v30
	v_lshlrev_b32_e32 v30, 16, v30
	v_mul_f32_e32 v80, v75, v80
	v_fmac_f32_e32 v80, v74, v30
	v_lshlrev_b32_e32 v30, 16, v31
	v_fmac_f32_e32 v80, v76, v30
	v_and_b32_e32 v31, 0xffff0000, v31
	v_fmac_f32_e32 v80, v77, v31
	v_and_b32_e32 v81, 0xffff0000, v32
	v_lshlrev_b32_e32 v32, 16, v32
	v_mul_f32_e32 v81, v75, v81
	v_fmac_f32_e32 v81, v74, v32
	v_lshlrev_b32_e32 v32, 16, v33
	v_fmac_f32_e32 v81, v76, v32
	v_and_b32_e32 v33, 0xffff0000, v33
	v_fmac_f32_e32 v81, v77, v33
	v_add_f32_dpp v78, v78, v78 quad_perm:[1,0,3,2] row_mask:0xf bank_mask:0xf bound_ctrl:1
	v_add_f32_dpp v79, v79, v79 quad_perm:[1,0,3,2] row_mask:0xf bank_mask:0xf bound_ctrl:1
	v_add_f32_dpp v80, v80, v80 quad_perm:[1,0,3,2] row_mask:0xf bank_mask:0xf bound_ctrl:1
	v_add_f32_dpp v81, v81, v81 quad_perm:[1,0,3,2] row_mask:0xf bank_mask:0xf bound_ctrl:1
	v_add_f32_dpp v78, v78, v78 quad_perm:[2,3,0,1] row_mask:0xf bank_mask:0xf bound_ctrl:1
	v_add_f32_dpp v79, v79, v79 quad_perm:[2,3,0,1] row_mask:0xf bank_mask:0xf bound_ctrl:1
	v_add_f32_dpp v80, v80, v80 quad_perm:[2,3,0,1] row_mask:0xf bank_mask:0xf bound_ctrl:1
	v_add_f32_dpp v81, v81, v81 quad_perm:[2,3,0,1] row_mask:0xf bank_mask:0xf bound_ctrl:1
	v_add_f32_dpp v78, v78, v78 row_half_mirror row_mask:0xf bank_mask:0xf bound_ctrl:1
	v_add_f32_dpp v79, v79, v79 row_half_mirror row_mask:0xf bank_mask:0xf bound_ctrl:1
	v_add_f32_dpp v80, v80, v80 row_half_mirror row_mask:0xf bank_mask:0xf bound_ctrl:1
	v_add_f32_dpp v81, v81, v81 row_half_mirror row_mask:0xf bank_mask:0xf bound_ctrl:1
	v_add_f32_dpp v78, v78, v78 row_mirror row_mask:0xf bank_mask:0xf bound_ctrl:1
	v_add_f32_dpp v79, v79, v79 row_mirror row_mask:0xf bank_mask:0xf bound_ctrl:1
	v_add_f32_dpp v80, v80, v80 row_mirror row_mask:0xf bank_mask:0xf bound_ctrl:1
	v_add_f32_dpp v81, v81, v81 row_mirror row_mask:0xf bank_mask:0xf bound_ctrl:1
	v_readlane_b32 s82, v78, 0
	v_readlane_b32 s83, v78, 16
	v_readlane_b32 s84, v78, 32
	v_readlane_b32 s85, v78, 48
	v_readlane_b32 s86, v79, 0
	v_readlane_b32 s87, v79, 16
	v_readlane_b32 s88, v79, 32
	v_readlane_b32 s89, v79, 48
	v_readlane_b32 s90, v80, 0
	v_readlane_b32 s91, v80, 16
	v_readlane_b32 s92, v80, 32
	v_readlane_b32 s93, v80, 48
	v_readlane_b32 s94, v81, 0
	v_readlane_b32 s95, v81, 16
	v_readlane_b32 s79, v81, 32
	v_readlane_b32 s80, v81, 48
	s_mov_b64 exec, s[26:27]
	v_mov_b32_e32 v9, s83
	v_add_f32_e32 v9, s82, v9
	v_add_f32_e32 v9, s84, v9
	v_add_f32_e32 v9, s85, v9
	s_lshl_b64 s[26:27], s[26:27], 1
	s_mov_b64 exec, s[26:27]
	v_mov_b32_e32 v9, s87
	v_add_f32_e32 v9, s86, v9
	v_add_f32_e32 v9, s88, v9
	v_add_f32_e32 v9, s89, v9
	s_lshl_b64 s[26:27], s[26:27], 1
	s_mov_b64 exec, s[26:27]
	v_mov_b32_e32 v9, s91
	v_add_f32_e32 v9, s90, v9
	v_add_f32_e32 v9, s92, v9
	v_add_f32_e32 v9, s93, v9
	s_lshl_b64 s[26:27], s[26:27], 1
	s_mov_b64 exec, s[26:27]
	v_mov_b32_e32 v9, s95
	v_add_f32_e32 v9, s94, v9
	v_add_f32_e32 v9, s79, v9
	v_add_f32_e32 v9, s80, v9
	s_lshl_b64 s[26:27], s[26:27], 1
	s_mov_b64 exec, -1
	s_waitcnt vmcnt(16)
	v_and_b32_e32 v78, 0xffff0000, v34
	v_lshlrev_b32_e32 v34, 16, v34
	v_mul_f32_e32 v78, v75, v78
	v_fmac_f32_e32 v78, v74, v34
	v_lshlrev_b32_e32 v34, 16, v35
	v_fmac_f32_e32 v78, v76, v34
	v_and_b32_e32 v35, 0xffff0000, v35
	v_fmac_f32_e32 v78, v77, v35
	v_and_b32_e32 v79, 0xffff0000, v36
	v_lshlrev_b32_e32 v36, 16, v36
	v_mul_f32_e32 v79, v75, v79
	v_fmac_f32_e32 v79, v74, v36
	v_lshlrev_b32_e32 v36, 16, v37
	v_fmac_f32_e32 v79, v76, v36
	v_and_b32_e32 v37, 0xffff0000, v37
	v_fmac_f32_e32 v79, v77, v37
	v_and_b32_e32 v80, 0xffff0000, v38
	v_lshlrev_b32_e32 v38, 16, v38
	v_mul_f32_e32 v80, v75, v80
	v_fmac_f32_e32 v80, v74, v38
	v_lshlrev_b32_e32 v38, 16, v39
	v_fmac_f32_e32 v80, v76, v38
	v_and_b32_e32 v39, 0xffff0000, v39
	v_fmac_f32_e32 v80, v77, v39
	v_and_b32_e32 v81, 0xffff0000, v40
	v_lshlrev_b32_e32 v40, 16, v40
	v_mul_f32_e32 v81, v75, v81
	v_fmac_f32_e32 v81, v74, v40
	v_lshlrev_b32_e32 v40, 16, v41
	v_fmac_f32_e32 v81, v76, v40
	v_and_b32_e32 v41, 0xffff0000, v41
	v_fmac_f32_e32 v81, v77, v41
	v_add_f32_dpp v78, v78, v78 quad_perm:[1,0,3,2] row_mask:0xf bank_mask:0xf bound_ctrl:1
	v_add_f32_dpp v79, v79, v79 quad_perm:[1,0,3,2] row_mask:0xf bank_mask:0xf bound_ctrl:1
	v_add_f32_dpp v80, v80, v80 quad_perm:[1,0,3,2] row_mask:0xf bank_mask:0xf bound_ctrl:1
	v_add_f32_dpp v81, v81, v81 quad_perm:[1,0,3,2] row_mask:0xf bank_mask:0xf bound_ctrl:1
	v_add_f32_dpp v78, v78, v78 quad_perm:[2,3,0,1] row_mask:0xf bank_mask:0xf bound_ctrl:1
	v_add_f32_dpp v79, v79, v79 quad_perm:[2,3,0,1] row_mask:0xf bank_mask:0xf bound_ctrl:1
	v_add_f32_dpp v80, v80, v80 quad_perm:[2,3,0,1] row_mask:0xf bank_mask:0xf bound_ctrl:1
	v_add_f32_dpp v81, v81, v81 quad_perm:[2,3,0,1] row_mask:0xf bank_mask:0xf bound_ctrl:1
	v_add_f32_dpp v78, v78, v78 row_half_mirror row_mask:0xf bank_mask:0xf bound_ctrl:1
	v_add_f32_dpp v79, v79, v79 row_half_mirror row_mask:0xf bank_mask:0xf bound_ctrl:1
	v_add_f32_dpp v80, v80, v80 row_half_mirror row_mask:0xf bank_mask:0xf bound_ctrl:1
	v_add_f32_dpp v81, v81, v81 row_half_mirror row_mask:0xf bank_mask:0xf bound_ctrl:1
	v_add_f32_dpp v78, v78, v78 row_mirror row_mask:0xf bank_mask:0xf bound_ctrl:1
	v_add_f32_dpp v79, v79, v79 row_mirror row_mask:0xf bank_mask:0xf bound_ctrl:1
	v_add_f32_dpp v80, v80, v80 row_mirror row_mask:0xf bank_mask:0xf bound_ctrl:1
	v_add_f32_dpp v81, v81, v81 row_mirror row_mask:0xf bank_mask:0xf bound_ctrl:1
	v_readlane_b32 s82, v78, 0
	v_readlane_b32 s83, v78, 16
	v_readlane_b32 s84, v78, 32
	v_readlane_b32 s85, v78, 48
	v_readlane_b32 s86, v79, 0
	v_readlane_b32 s87, v79, 16
	v_readlane_b32 s88, v79, 32
	v_readlane_b32 s89, v79, 48
	v_readlane_b32 s90, v80, 0
	v_readlane_b32 s91, v80, 16
	v_readlane_b32 s92, v80, 32
	v_readlane_b32 s93, v80, 48
	v_readlane_b32 s94, v81, 0
	v_readlane_b32 s95, v81, 16
	v_readlane_b32 s79, v81, 32
	v_readlane_b32 s80, v81, 48
	s_mov_b64 exec, s[26:27]
	v_mov_b32_e32 v9, s83
	v_add_f32_e32 v9, s82, v9
	v_add_f32_e32 v9, s84, v9
	v_add_f32_e32 v9, s85, v9
	s_lshl_b64 s[26:27], s[26:27], 1
	s_mov_b64 exec, s[26:27]
	v_mov_b32_e32 v9, s87
	v_add_f32_e32 v9, s86, v9
	v_add_f32_e32 v9, s88, v9
	v_add_f32_e32 v9, s89, v9
	s_lshl_b64 s[26:27], s[26:27], 1
	s_mov_b64 exec, s[26:27]
	v_mov_b32_e32 v9, s91
	v_add_f32_e32 v9, s90, v9
	v_add_f32_e32 v9, s92, v9
	v_add_f32_e32 v9, s93, v9
	s_lshl_b64 s[26:27], s[26:27], 1
	s_mov_b64 exec, s[26:27]
	v_mov_b32_e32 v9, s95
	v_add_f32_e32 v9, s94, v9
	v_add_f32_e32 v9, s79, v9
	v_add_f32_e32 v9, s80, v9
	s_lshl_b64 s[26:27], s[26:27], 1
	s_mov_b64 exec, -1
	s_waitcnt vmcnt(12)
	v_and_b32_e32 v78, 0xffff0000, v42
	v_lshlrev_b32_e32 v42, 16, v42
	v_mul_f32_e32 v78, v75, v78
	v_fmac_f32_e32 v78, v74, v42
	v_lshlrev_b32_e32 v42, 16, v43
	v_fmac_f32_e32 v78, v76, v42
	v_and_b32_e32 v43, 0xffff0000, v43
	v_fmac_f32_e32 v78, v77, v43
	v_and_b32_e32 v79, 0xffff0000, v44
	v_lshlrev_b32_e32 v44, 16, v44
	v_mul_f32_e32 v79, v75, v79
	v_fmac_f32_e32 v79, v74, v44
	v_lshlrev_b32_e32 v44, 16, v45
	v_fmac_f32_e32 v79, v76, v44
	v_and_b32_e32 v45, 0xffff0000, v45
	v_fmac_f32_e32 v79, v77, v45
	v_and_b32_e32 v80, 0xffff0000, v46
	v_lshlrev_b32_e32 v46, 16, v46
	v_mul_f32_e32 v80, v75, v80
	v_fmac_f32_e32 v80, v74, v46
	v_lshlrev_b32_e32 v46, 16, v47
	v_fmac_f32_e32 v80, v76, v46
	v_and_b32_e32 v47, 0xffff0000, v47
	v_fmac_f32_e32 v80, v77, v47
	v_and_b32_e32 v81, 0xffff0000, v48
	v_lshlrev_b32_e32 v48, 16, v48
	v_mul_f32_e32 v81, v75, v81
	v_fmac_f32_e32 v81, v74, v48
	v_lshlrev_b32_e32 v48, 16, v49
	v_fmac_f32_e32 v81, v76, v48
	v_and_b32_e32 v49, 0xffff0000, v49
	v_fmac_f32_e32 v81, v77, v49
	v_add_f32_dpp v78, v78, v78 quad_perm:[1,0,3,2] row_mask:0xf bank_mask:0xf bound_ctrl:1
	v_add_f32_dpp v79, v79, v79 quad_perm:[1,0,3,2] row_mask:0xf bank_mask:0xf bound_ctrl:1
	v_add_f32_dpp v80, v80, v80 quad_perm:[1,0,3,2] row_mask:0xf bank_mask:0xf bound_ctrl:1
	v_add_f32_dpp v81, v81, v81 quad_perm:[1,0,3,2] row_mask:0xf bank_mask:0xf bound_ctrl:1
	v_add_f32_dpp v78, v78, v78 quad_perm:[2,3,0,1] row_mask:0xf bank_mask:0xf bound_ctrl:1
	v_add_f32_dpp v79, v79, v79 quad_perm:[2,3,0,1] row_mask:0xf bank_mask:0xf bound_ctrl:1
	v_add_f32_dpp v80, v80, v80 quad_perm:[2,3,0,1] row_mask:0xf bank_mask:0xf bound_ctrl:1
	v_add_f32_dpp v81, v81, v81 quad_perm:[2,3,0,1] row_mask:0xf bank_mask:0xf bound_ctrl:1
	v_add_f32_dpp v78, v78, v78 row_half_mirror row_mask:0xf bank_mask:0xf bound_ctrl:1
	v_add_f32_dpp v79, v79, v79 row_half_mirror row_mask:0xf bank_mask:0xf bound_ctrl:1
	v_add_f32_dpp v80, v80, v80 row_half_mirror row_mask:0xf bank_mask:0xf bound_ctrl:1
	v_add_f32_dpp v81, v81, v81 row_half_mirror row_mask:0xf bank_mask:0xf bound_ctrl:1
	v_add_f32_dpp v78, v78, v78 row_mirror row_mask:0xf bank_mask:0xf bound_ctrl:1
	v_add_f32_dpp v79, v79, v79 row_mirror row_mask:0xf bank_mask:0xf bound_ctrl:1
	v_add_f32_dpp v80, v80, v80 row_mirror row_mask:0xf bank_mask:0xf bound_ctrl:1
	v_add_f32_dpp v81, v81, v81 row_mirror row_mask:0xf bank_mask:0xf bound_ctrl:1
	v_readlane_b32 s82, v78, 0
	v_readlane_b32 s83, v78, 16
	v_readlane_b32 s84, v78, 32
	v_readlane_b32 s85, v78, 48
	v_readlane_b32 s86, v79, 0
	v_readlane_b32 s87, v79, 16
	v_readlane_b32 s88, v79, 32
	v_readlane_b32 s89, v79, 48
	v_readlane_b32 s90, v80, 0
	v_readlane_b32 s91, v80, 16
	v_readlane_b32 s92, v80, 32
	v_readlane_b32 s93, v80, 48
	v_readlane_b32 s94, v81, 0
	v_readlane_b32 s95, v81, 16
	v_readlane_b32 s79, v81, 32
	v_readlane_b32 s80, v81, 48
	s_mov_b64 exec, s[26:27]
	v_mov_b32_e32 v9, s83
	v_add_f32_e32 v9, s82, v9
	v_add_f32_e32 v9, s84, v9
	v_add_f32_e32 v9, s85, v9
	s_lshl_b64 s[26:27], s[26:27], 1
	s_mov_b64 exec, s[26:27]
	v_mov_b32_e32 v9, s87
	v_add_f32_e32 v9, s86, v9
	v_add_f32_e32 v9, s88, v9
	v_add_f32_e32 v9, s89, v9
	s_lshl_b64 s[26:27], s[26:27], 1
	s_mov_b64 exec, s[26:27]
	v_mov_b32_e32 v9, s91
	v_add_f32_e32 v9, s90, v9
	v_add_f32_e32 v9, s92, v9
	v_add_f32_e32 v9, s93, v9
	s_lshl_b64 s[26:27], s[26:27], 1
	s_mov_b64 exec, s[26:27]
	v_mov_b32_e32 v9, s95
	v_add_f32_e32 v9, s94, v9
	v_add_f32_e32 v9, s79, v9
	v_add_f32_e32 v9, s80, v9
	s_lshl_b64 s[26:27], s[26:27], 1
	s_mov_b64 exec, -1
	s_waitcnt vmcnt(8)
	v_and_b32_e32 v78, 0xffff0000, v50
	v_lshlrev_b32_e32 v50, 16, v50
	v_mul_f32_e32 v78, v75, v78
	v_fmac_f32_e32 v78, v74, v50
	v_lshlrev_b32_e32 v50, 16, v51
	v_fmac_f32_e32 v78, v76, v50
	v_and_b32_e32 v51, 0xffff0000, v51
	v_fmac_f32_e32 v78, v77, v51
	v_and_b32_e32 v79, 0xffff0000, v52
	v_lshlrev_b32_e32 v52, 16, v52
	v_mul_f32_e32 v79, v75, v79
	v_fmac_f32_e32 v79, v74, v52
	v_lshlrev_b32_e32 v52, 16, v53
	v_fmac_f32_e32 v79, v76, v52
	v_and_b32_e32 v53, 0xffff0000, v53
	v_fmac_f32_e32 v79, v77, v53
	v_and_b32_e32 v80, 0xffff0000, v54
	v_lshlrev_b32_e32 v54, 16, v54
	v_mul_f32_e32 v80, v75, v80
	v_fmac_f32_e32 v80, v74, v54
	v_lshlrev_b32_e32 v54, 16, v55
	v_fmac_f32_e32 v80, v76, v54
	v_and_b32_e32 v55, 0xffff0000, v55
	v_fmac_f32_e32 v80, v77, v55
	v_and_b32_e32 v81, 0xffff0000, v56
	v_lshlrev_b32_e32 v56, 16, v56
	v_mul_f32_e32 v81, v75, v81
	v_fmac_f32_e32 v81, v74, v56
	v_lshlrev_b32_e32 v56, 16, v57
	v_fmac_f32_e32 v81, v76, v56
	v_and_b32_e32 v57, 0xffff0000, v57
	v_fmac_f32_e32 v81, v77, v57
	v_add_f32_dpp v78, v78, v78 quad_perm:[1,0,3,2] row_mask:0xf bank_mask:0xf bound_ctrl:1
	v_add_f32_dpp v79, v79, v79 quad_perm:[1,0,3,2] row_mask:0xf bank_mask:0xf bound_ctrl:1
	v_add_f32_dpp v80, v80, v80 quad_perm:[1,0,3,2] row_mask:0xf bank_mask:0xf bound_ctrl:1
	v_add_f32_dpp v81, v81, v81 quad_perm:[1,0,3,2] row_mask:0xf bank_mask:0xf bound_ctrl:1
	v_add_f32_dpp v78, v78, v78 quad_perm:[2,3,0,1] row_mask:0xf bank_mask:0xf bound_ctrl:1
	v_add_f32_dpp v79, v79, v79 quad_perm:[2,3,0,1] row_mask:0xf bank_mask:0xf bound_ctrl:1
	v_add_f32_dpp v80, v80, v80 quad_perm:[2,3,0,1] row_mask:0xf bank_mask:0xf bound_ctrl:1
	v_add_f32_dpp v81, v81, v81 quad_perm:[2,3,0,1] row_mask:0xf bank_mask:0xf bound_ctrl:1
	v_add_f32_dpp v78, v78, v78 row_half_mirror row_mask:0xf bank_mask:0xf bound_ctrl:1
	v_add_f32_dpp v79, v79, v79 row_half_mirror row_mask:0xf bank_mask:0xf bound_ctrl:1
	v_add_f32_dpp v80, v80, v80 row_half_mirror row_mask:0xf bank_mask:0xf bound_ctrl:1
	v_add_f32_dpp v81, v81, v81 row_half_mirror row_mask:0xf bank_mask:0xf bound_ctrl:1
	v_add_f32_dpp v78, v78, v78 row_mirror row_mask:0xf bank_mask:0xf bound_ctrl:1
	v_add_f32_dpp v79, v79, v79 row_mirror row_mask:0xf bank_mask:0xf bound_ctrl:1
	v_add_f32_dpp v80, v80, v80 row_mirror row_mask:0xf bank_mask:0xf bound_ctrl:1
	v_add_f32_dpp v81, v81, v81 row_mirror row_mask:0xf bank_mask:0xf bound_ctrl:1
	v_readlane_b32 s82, v78, 0
	v_readlane_b32 s83, v78, 16
	v_readlane_b32 s84, v78, 32
	v_readlane_b32 s85, v78, 48
	v_readlane_b32 s86, v79, 0
	v_readlane_b32 s87, v79, 16
	v_readlane_b32 s88, v79, 32
	v_readlane_b32 s89, v79, 48
	v_readlane_b32 s90, v80, 0
	v_readlane_b32 s91, v80, 16
	v_readlane_b32 s92, v80, 32
	v_readlane_b32 s93, v80, 48
	v_readlane_b32 s94, v81, 0
	v_readlane_b32 s95, v81, 16
	v_readlane_b32 s79, v81, 32
	v_readlane_b32 s80, v81, 48
	s_mov_b64 exec, s[26:27]
	v_mov_b32_e32 v9, s83
	v_add_f32_e32 v9, s82, v9
	v_add_f32_e32 v9, s84, v9
	v_add_f32_e32 v9, s85, v9
	s_lshl_b64 s[26:27], s[26:27], 1
	s_mov_b64 exec, s[26:27]
	v_mov_b32_e32 v9, s87
	v_add_f32_e32 v9, s86, v9
	v_add_f32_e32 v9, s88, v9
	v_add_f32_e32 v9, s89, v9
	s_lshl_b64 s[26:27], s[26:27], 1
	s_mov_b64 exec, s[26:27]
	v_mov_b32_e32 v9, s91
	v_add_f32_e32 v9, s90, v9
	v_add_f32_e32 v9, s92, v9
	v_add_f32_e32 v9, s93, v9
	s_lshl_b64 s[26:27], s[26:27], 1
	s_mov_b64 exec, s[26:27]
	v_mov_b32_e32 v9, s95
	v_add_f32_e32 v9, s94, v9
	v_add_f32_e32 v9, s79, v9
	v_add_f32_e32 v9, s80, v9
	s_lshl_b64 s[26:27], s[26:27], 1
	s_mov_b64 exec, -1
	s_waitcnt vmcnt(4)
	v_and_b32_e32 v78, 0xffff0000, v58
	v_lshlrev_b32_e32 v58, 16, v58
	v_mul_f32_e32 v78, v75, v78
	v_fmac_f32_e32 v78, v74, v58
	v_lshlrev_b32_e32 v58, 16, v59
	v_fmac_f32_e32 v78, v76, v58
	v_and_b32_e32 v59, 0xffff0000, v59
	v_fmac_f32_e32 v78, v77, v59
	v_and_b32_e32 v79, 0xffff0000, v60
	v_lshlrev_b32_e32 v60, 16, v60
	v_mul_f32_e32 v79, v75, v79
	v_fmac_f32_e32 v79, v74, v60
	v_lshlrev_b32_e32 v60, 16, v61
	v_fmac_f32_e32 v79, v76, v60
	v_and_b32_e32 v61, 0xffff0000, v61
	v_fmac_f32_e32 v79, v77, v61
	v_and_b32_e32 v80, 0xffff0000, v62
	v_lshlrev_b32_e32 v62, 16, v62
	v_mul_f32_e32 v80, v75, v80
	v_fmac_f32_e32 v80, v74, v62
	v_lshlrev_b32_e32 v62, 16, v63
	v_fmac_f32_e32 v80, v76, v62
	v_and_b32_e32 v63, 0xffff0000, v63
	v_fmac_f32_e32 v80, v77, v63
	v_and_b32_e32 v81, 0xffff0000, v64
	v_lshlrev_b32_e32 v64, 16, v64
	v_mul_f32_e32 v81, v75, v81
	v_fmac_f32_e32 v81, v74, v64
	v_lshlrev_b32_e32 v64, 16, v65
	v_fmac_f32_e32 v81, v76, v64
	v_and_b32_e32 v65, 0xffff0000, v65
	v_fmac_f32_e32 v81, v77, v65
	v_add_f32_dpp v78, v78, v78 quad_perm:[1,0,3,2] row_mask:0xf bank_mask:0xf bound_ctrl:1
	v_add_f32_dpp v79, v79, v79 quad_perm:[1,0,3,2] row_mask:0xf bank_mask:0xf bound_ctrl:1
	v_add_f32_dpp v80, v80, v80 quad_perm:[1,0,3,2] row_mask:0xf bank_mask:0xf bound_ctrl:1
	v_add_f32_dpp v81, v81, v81 quad_perm:[1,0,3,2] row_mask:0xf bank_mask:0xf bound_ctrl:1
	v_add_f32_dpp v78, v78, v78 quad_perm:[2,3,0,1] row_mask:0xf bank_mask:0xf bound_ctrl:1
	v_add_f32_dpp v79, v79, v79 quad_perm:[2,3,0,1] row_mask:0xf bank_mask:0xf bound_ctrl:1
	v_add_f32_dpp v80, v80, v80 quad_perm:[2,3,0,1] row_mask:0xf bank_mask:0xf bound_ctrl:1
	v_add_f32_dpp v81, v81, v81 quad_perm:[2,3,0,1] row_mask:0xf bank_mask:0xf bound_ctrl:1
	v_add_f32_dpp v78, v78, v78 row_half_mirror row_mask:0xf bank_mask:0xf bound_ctrl:1
	v_add_f32_dpp v79, v79, v79 row_half_mirror row_mask:0xf bank_mask:0xf bound_ctrl:1
	v_add_f32_dpp v80, v80, v80 row_half_mirror row_mask:0xf bank_mask:0xf bound_ctrl:1
	v_add_f32_dpp v81, v81, v81 row_half_mirror row_mask:0xf bank_mask:0xf bound_ctrl:1
	v_add_f32_dpp v78, v78, v78 row_mirror row_mask:0xf bank_mask:0xf bound_ctrl:1
	v_add_f32_dpp v79, v79, v79 row_mirror row_mask:0xf bank_mask:0xf bound_ctrl:1
	v_add_f32_dpp v80, v80, v80 row_mirror row_mask:0xf bank_mask:0xf bound_ctrl:1
	v_add_f32_dpp v81, v81, v81 row_mirror row_mask:0xf bank_mask:0xf bound_ctrl:1
	v_readlane_b32 s82, v78, 0
	v_readlane_b32 s83, v78, 16
	v_readlane_b32 s84, v78, 32
	v_readlane_b32 s85, v78, 48
	v_readlane_b32 s86, v79, 0
	v_readlane_b32 s87, v79, 16
	v_readlane_b32 s88, v79, 32
	v_readlane_b32 s89, v79, 48
	v_readlane_b32 s90, v80, 0
	v_readlane_b32 s91, v80, 16
	v_readlane_b32 s92, v80, 32
	v_readlane_b32 s93, v80, 48
	v_readlane_b32 s94, v81, 0
	v_readlane_b32 s95, v81, 16
	v_readlane_b32 s79, v81, 32
	v_readlane_b32 s80, v81, 48
	s_mov_b64 exec, s[26:27]
	v_mov_b32_e32 v9, s83
	v_add_f32_e32 v9, s82, v9
	v_add_f32_e32 v9, s84, v9
	v_add_f32_e32 v9, s85, v9
	s_lshl_b64 s[26:27], s[26:27], 1
	s_mov_b64 exec, s[26:27]
	v_mov_b32_e32 v9, s87
	v_add_f32_e32 v9, s86, v9
	v_add_f32_e32 v9, s88, v9
	v_add_f32_e32 v9, s89, v9
	s_lshl_b64 s[26:27], s[26:27], 1
	s_mov_b64 exec, s[26:27]
	v_mov_b32_e32 v9, s91
	v_add_f32_e32 v9, s90, v9
	v_add_f32_e32 v9, s92, v9
	v_add_f32_e32 v9, s93, v9
	s_lshl_b64 s[26:27], s[26:27], 1
	s_mov_b64 exec, s[26:27]
	v_mov_b32_e32 v9, s95
	v_add_f32_e32 v9, s94, v9
	v_add_f32_e32 v9, s79, v9
	v_add_f32_e32 v9, s80, v9
	s_lshl_b64 s[26:27], s[26:27], 1
	s_mov_b64 exec, -1
	s_waitcnt vmcnt(0)
	v_and_b32_e32 v78, 0xffff0000, v66
	v_lshlrev_b32_e32 v66, 16, v66
	v_mul_f32_e32 v78, v75, v78
	v_fmac_f32_e32 v78, v74, v66
	v_lshlrev_b32_e32 v66, 16, v67
	v_fmac_f32_e32 v78, v76, v66
	v_and_b32_e32 v67, 0xffff0000, v67
	v_fmac_f32_e32 v78, v77, v67
	v_and_b32_e32 v79, 0xffff0000, v68
	v_lshlrev_b32_e32 v68, 16, v68
	v_mul_f32_e32 v79, v75, v79
	v_fmac_f32_e32 v79, v74, v68
	v_lshlrev_b32_e32 v68, 16, v69
	v_fmac_f32_e32 v79, v76, v68
	v_and_b32_e32 v69, 0xffff0000, v69
	v_fmac_f32_e32 v79, v77, v69
	v_and_b32_e32 v80, 0xffff0000, v70
	v_lshlrev_b32_e32 v70, 16, v70
	v_mul_f32_e32 v80, v75, v80
	v_fmac_f32_e32 v80, v74, v70
	v_lshlrev_b32_e32 v70, 16, v71
	v_fmac_f32_e32 v80, v76, v70
	v_and_b32_e32 v71, 0xffff0000, v71
	v_fmac_f32_e32 v80, v77, v71
	v_and_b32_e32 v81, 0xffff0000, v72
	v_lshlrev_b32_e32 v72, 16, v72
	v_mul_f32_e32 v81, v75, v81
	v_fmac_f32_e32 v81, v74, v72
	v_lshlrev_b32_e32 v72, 16, v73
	v_fmac_f32_e32 v81, v76, v72
	v_and_b32_e32 v73, 0xffff0000, v73
	v_fmac_f32_e32 v81, v77, v73
	v_add_f32_dpp v78, v78, v78 quad_perm:[1,0,3,2] row_mask:0xf bank_mask:0xf bound_ctrl:1
	v_add_f32_dpp v79, v79, v79 quad_perm:[1,0,3,2] row_mask:0xf bank_mask:0xf bound_ctrl:1
	v_add_f32_dpp v80, v80, v80 quad_perm:[1,0,3,2] row_mask:0xf bank_mask:0xf bound_ctrl:1
	v_add_f32_dpp v81, v81, v81 quad_perm:[1,0,3,2] row_mask:0xf bank_mask:0xf bound_ctrl:1
	v_add_f32_dpp v78, v78, v78 quad_perm:[2,3,0,1] row_mask:0xf bank_mask:0xf bound_ctrl:1
	v_add_f32_dpp v79, v79, v79 quad_perm:[2,3,0,1] row_mask:0xf bank_mask:0xf bound_ctrl:1
	v_add_f32_dpp v80, v80, v80 quad_perm:[2,3,0,1] row_mask:0xf bank_mask:0xf bound_ctrl:1
	v_add_f32_dpp v81, v81, v81 quad_perm:[2,3,0,1] row_mask:0xf bank_mask:0xf bound_ctrl:1
	v_add_f32_dpp v78, v78, v78 row_half_mirror row_mask:0xf bank_mask:0xf bound_ctrl:1
	v_add_f32_dpp v79, v79, v79 row_half_mirror row_mask:0xf bank_mask:0xf bound_ctrl:1
	v_add_f32_dpp v80, v80, v80 row_half_mirror row_mask:0xf bank_mask:0xf bound_ctrl:1
	v_add_f32_dpp v81, v81, v81 row_half_mirror row_mask:0xf bank_mask:0xf bound_ctrl:1
	v_add_f32_dpp v78, v78, v78 row_mirror row_mask:0xf bank_mask:0xf bound_ctrl:1
	v_add_f32_dpp v79, v79, v79 row_mirror row_mask:0xf bank_mask:0xf bound_ctrl:1
	v_add_f32_dpp v80, v80, v80 row_mirror row_mask:0xf bank_mask:0xf bound_ctrl:1
	v_add_f32_dpp v81, v81, v81 row_mirror row_mask:0xf bank_mask:0xf bound_ctrl:1
	v_readlane_b32 s82, v78, 0
	v_readlane_b32 s83, v78, 16
	v_readlane_b32 s84, v78, 32
	v_readlane_b32 s85, v78, 48
	v_readlane_b32 s86, v79, 0
	v_readlane_b32 s87, v79, 16
	v_readlane_b32 s88, v79, 32
	v_readlane_b32 s89, v79, 48
	v_readlane_b32 s90, v80, 0
	v_readlane_b32 s91, v80, 16
	v_readlane_b32 s92, v80, 32
	v_readlane_b32 s93, v80, 48
	v_readlane_b32 s94, v81, 0
	v_readlane_b32 s95, v81, 16
	v_readlane_b32 s79, v81, 32
	v_readlane_b32 s80, v81, 48
	s_mov_b64 exec, s[26:27]
	v_mov_b32_e32 v9, s83
	v_add_f32_e32 v9, s82, v9
	v_add_f32_e32 v9, s84, v9
	v_add_f32_e32 v9, s85, v9
	s_lshl_b64 s[26:27], s[26:27], 1
	s_mov_b64 exec, s[26:27]
	v_mov_b32_e32 v9, s87
	v_add_f32_e32 v9, s86, v9
	v_add_f32_e32 v9, s88, v9
	v_add_f32_e32 v9, s89, v9
	s_lshl_b64 s[26:27], s[26:27], 1
	s_mov_b64 exec, s[26:27]
	v_mov_b32_e32 v9, s91
	v_add_f32_e32 v9, s90, v9
	v_add_f32_e32 v9, s92, v9
	v_add_f32_e32 v9, s93, v9
	s_lshl_b64 s[26:27], s[26:27], 1
	s_mov_b64 exec, s[26:27]
	v_mov_b32_e32 v9, s95
	v_add_f32_e32 v9, s94, v9
	v_add_f32_e32 v9, s79, v9
	v_add_f32_e32 v9, s80, v9
	s_lshl_b64 s[26:27], s[26:27], 1
	s_mov_b64 exec, -1
	v_and_b32_e32 v4, 63, v182
	v_lshl_add_u32 v8, v4, 2, s24
	s_mov_b32 exec_hi, 0
	ds_write_b32 v8, v9
	s_mov_b64 exec, -1
